# EpiRes residual epilogue: loads 3 row-groups deep, stores after last wait; sample-attn K tile loaded coalesced via LDS staging; mLSTM scan loads batched 16 chunks
# speedup vs baseline: 1.0119x; 1.0119x over previous
.LBB0_634:
	s_mov_b64 s[14:15], 0x1800
	s_mov_b64 s[16:17], 0x40800
	s_mov_b64 s[18:19], 0x28000
	s_mov_b64 s[20:21], 32
	s_mov_b64 s[22:23], 0x1519d000
	v_lshl_add_u64 v[14:15], s[88:89], 0, v[12:13]
	v_lshl_add_u64 v[14:15], v[14:15], 0, s[22:23]
	s_mov_b64 s[22:23], 0x1525d000
	v_lshl_add_u64 v[16:17], s[88:89], 0, v[10:11]
	v_lshl_add_u64 v[16:17], v[16:17], 0, s[22:23]
	s_mov_b64 s[22:23], 0x1729d000
	v_lshl_add_u64 v[18:19], s[88:89], 0, v[8:9]
	v_lshl_add_u64 v[18:19], v[18:19], 0, s[22:23]
	s_mov_b64 s[22:23], 0x1869d000
	v_lshl_add_u64 v[22:23], s[88:89], 0, v[6:7]
	v_lshl_add_u64 v[22:23], v[22:23], 0, s[22:23]
.Lscan_loop:
	global_load_dword v28, v[14:15], off offset:252
	global_load_dword v44, v[14:15], off offset:764
	global_load_dword v60, v[16:17], off
	v_lshl_add_u64 v[14:15], v[14:15], 0, s[14:15]
	v_lshl_add_u64 v[16:17], v[16:17], 0, s[16:17]
	global_load_dword v29, v[14:15], off offset:252
	global_load_dword v45, v[14:15], off offset:764
	global_load_dword v61, v[16:17], off
	v_lshl_add_u64 v[14:15], v[14:15], 0, s[14:15]
	v_lshl_add_u64 v[16:17], v[16:17], 0, s[16:17]
	global_load_dword v30, v[14:15], off offset:252
	global_load_dword v46, v[14:15], off offset:764
	global_load_dword v62, v[16:17], off
	v_lshl_add_u64 v[14:15], v[14:15], 0, s[14:15]
	v_lshl_add_u64 v[16:17], v[16:17], 0, s[16:17]
	global_load_dword v31, v[14:15], off offset:252
	global_load_dword v47, v[14:15], off offset:764
	global_load_dword v63, v[16:17], off
	v_lshl_add_u64 v[14:15], v[14:15], 0, s[14:15]
	v_lshl_add_u64 v[16:17], v[16:17], 0, s[16:17]
	global_load_dword v32, v[14:15], off offset:252
	global_load_dword v48, v[14:15], off offset:764
	global_load_dword v64, v[16:17], off
	v_lshl_add_u64 v[14:15], v[14:15], 0, s[14:15]
	v_lshl_add_u64 v[16:17], v[16:17], 0, s[16:17]
	global_load_dword v33, v[14:15], off offset:252
	global_load_dword v49, v[14:15], off offset:764
	global_load_dword v65, v[16:17], off
	v_lshl_add_u64 v[14:15], v[14:15], 0, s[14:15]
	v_lshl_add_u64 v[16:17], v[16:17], 0, s[16:17]
	global_load_dword v34, v[14:15], off offset:252
	global_load_dword v50, v[14:15], off offset:764
	global_load_dword v66, v[16:17], off
	v_lshl_add_u64 v[14:15], v[14:15], 0, s[14:15]
	v_lshl_add_u64 v[16:17], v[16:17], 0, s[16:17]
	global_load_dword v35, v[14:15], off offset:252
	global_load_dword v51, v[14:15], off offset:764
	global_load_dword v67, v[16:17], off
	v_lshl_add_u64 v[14:15], v[14:15], 0, s[14:15]
	v_lshl_add_u64 v[16:17], v[16:17], 0, s[16:17]
	global_load_dword v36, v[14:15], off offset:252
	global_load_dword v52, v[14:15], off offset:764
	global_load_dword v68, v[16:17], off
	v_lshl_add_u64 v[14:15], v[14:15], 0, s[14:15]
	v_lshl_add_u64 v[16:17], v[16:17], 0, s[16:17]
	global_load_dword v37, v[14:15], off offset:252
	global_load_dword v53, v[14:15], off offset:764
	global_load_dword v69, v[16:17], off
	v_lshl_add_u64 v[14:15], v[14:15], 0, s[14:15]
	v_lshl_add_u64 v[16:17], v[16:17], 0, s[16:17]
	global_load_dword v38, v[14:15], off offset:252
	global_load_dword v54, v[14:15], off offset:764
	global_load_dword v70, v[16:17], off
	v_lshl_add_u64 v[14:15], v[14:15], 0, s[14:15]
	v_lshl_add_u64 v[16:17], v[16:17], 0, s[16:17]
	global_load_dword v39, v[14:15], off offset:252
	global_load_dword v55, v[14:15], off offset:764
	global_load_dword v71, v[16:17], off
	v_lshl_add_u64 v[14:15], v[14:15], 0, s[14:15]
	v_lshl_add_u64 v[16:17], v[16:17], 0, s[16:17]
	global_load_dword v40, v[14:15], off offset:252
	global_load_dword v56, v[14:15], off offset:764
	global_load_dword v72, v[16:17], off
	v_lshl_add_u64 v[14:15], v[14:15], 0, s[14:15]
	v_lshl_add_u64 v[16:17], v[16:17], 0, s[16:17]
	global_load_dword v41, v[14:15], off offset:252
	global_load_dword v57, v[14:15], off offset:764
	global_load_dword v73, v[16:17], off
	v_lshl_add_u64 v[14:15], v[14:15], 0, s[14:15]
	v_lshl_add_u64 v[16:17], v[16:17], 0, s[16:17]
	global_load_dword v42, v[14:15], off offset:252
	global_load_dword v58, v[14:15], off offset:764
	global_load_dword v74, v[16:17], off
	v_lshl_add_u64 v[14:15], v[14:15], 0, s[14:15]
	v_lshl_add_u64 v[16:17], v[16:17], 0, s[16:17]
	global_load_dword v43, v[14:15], off offset:252
	global_load_dword v59, v[14:15], off offset:764
	global_load_dword v75, v[16:17], off
	v_lshl_add_u64 v[14:15], v[14:15], 0, s[14:15]
	v_lshl_add_u64 v[16:17], v[16:17], 0, s[16:17]
	v_bfe_u32 v24, v20, 16, 1
	v_add3_u32 v24, v20, v24, s73
	global_store_short_d16_hi v[18:19], v24, off
	s_and_saveexec_b64 s[10:11], s[8:9]
	s_cbranch_execz .Lscan_ms_0
	global_store_dword v[22:23], v5, off
.Lscan_ms_0:
	s_or_b64 exec, exec, s[10:11]
	v_lshl_add_u64 v[18:19], v[18:19], 0, s[18:19]
	v_lshl_add_u64 v[22:23], v[22:23], 0, s[20:21]
	s_waitcnt vmcnt(46)
	v_add_f32_e32 v25, v28, v44
	v_add_f32_e32 v24, v5, v28
	v_max_f32_e32 v5, v24, v25
	v_sub_f32_e32 v25, v25, v5
	v_sub_f32_e32 v24, v24, v5
	v_mul_f32_e32 v25, 0x3fb8aa3b, v25
	v_mul_f32_e32 v24, 0x3fb8aa3b, v24
	v_exp_f32_e32 v25, v25
	v_exp_f32_e32 v24, v24
	s_nop 0
	v_mul_f32_e32 v26, v60, v25
	v_fma_f32 v20, v20, v24, v26
	v_bfe_u32 v24, v20, 16, 1
	v_add3_u32 v24, v20, v24, s73
	global_store_short_d16_hi v[18:19], v24, off
	s_and_saveexec_b64 s[10:11], s[8:9]
	s_cbranch_execz .Lscan_ms_1
	global_store_dword v[22:23], v5, off
.Lscan_ms_1:
	s_or_b64 exec, exec, s[10:11]
	v_lshl_add_u64 v[18:19], v[18:19], 0, s[18:19]
	v_lshl_add_u64 v[22:23], v[22:23], 0, s[20:21]
	s_waitcnt vmcnt(44)
	v_add_f32_e32 v25, v29, v45
	v_add_f32_e32 v24, v5, v29
	v_max_f32_e32 v5, v24, v25
	v_sub_f32_e32 v25, v25, v5
	v_sub_f32_e32 v24, v24, v5
	v_mul_f32_e32 v25, 0x3fb8aa3b, v25
	v_mul_f32_e32 v24, 0x3fb8aa3b, v24
	v_exp_f32_e32 v25, v25
	v_exp_f32_e32 v24, v24
	s_nop 0
	v_mul_f32_e32 v26, v61, v25
	v_fma_f32 v20, v20, v24, v26
	v_bfe_u32 v24, v20, 16, 1
	v_add3_u32 v24, v20, v24, s73
	global_store_short_d16_hi v[18:19], v24, off
	s_and_saveexec_b64 s[10:11], s[8:9]
	s_cbranch_execz .Lscan_ms_2
	global_store_dword v[22:23], v5, off
.Lscan_ms_2:
	s_or_b64 exec, exec, s[10:11]
	v_lshl_add_u64 v[18:19], v[18:19], 0, s[18:19]
	v_lshl_add_u64 v[22:23], v[22:23], 0, s[20:21]
	s_waitcnt vmcnt(42)
	v_add_f32_e32 v25, v30, v46
	v_add_f32_e32 v24, v5, v30
	v_max_f32_e32 v5, v24, v25
	v_sub_f32_e32 v25, v25, v5
	v_sub_f32_e32 v24, v24, v5
	v_mul_f32_e32 v25, 0x3fb8aa3b, v25
	v_mul_f32_e32 v24, 0x3fb8aa3b, v24
	v_exp_f32_e32 v25, v25
	v_exp_f32_e32 v24, v24
	s_nop 0
	v_mul_f32_e32 v26, v62, v25
	v_fma_f32 v20, v20, v24, v26
	v_bfe_u32 v24, v20, 16, 1
	v_add3_u32 v24, v20, v24, s73
	global_store_short_d16_hi v[18:19], v24, off
	s_and_saveexec_b64 s[10:11], s[8:9]
	s_cbranch_execz .Lscan_ms_3
	global_store_dword v[22:23], v5, off
.Lscan_ms_3:
	s_or_b64 exec, exec, s[10:11]
	v_lshl_add_u64 v[18:19], v[18:19], 0, s[18:19]
	v_lshl_add_u64 v[22:23], v[22:23], 0, s[20:21]
	s_waitcnt vmcnt(40)
	v_add_f32_e32 v25, v31, v47
	v_add_f32_e32 v24, v5, v31
	v_max_f32_e32 v5, v24, v25
	v_sub_f32_e32 v25, v25, v5
	v_sub_f32_e32 v24, v24, v5
	v_mul_f32_e32 v25, 0x3fb8aa3b, v25
	v_mul_f32_e32 v24, 0x3fb8aa3b, v24
	v_exp_f32_e32 v25, v25
	v_exp_f32_e32 v24, v24
	s_nop 0
	v_mul_f32_e32 v26, v63, v25
	v_fma_f32 v20, v20, v24, v26
	v_bfe_u32 v24, v20, 16, 1
	v_add3_u32 v24, v20, v24, s73
	global_store_short_d16_hi v[18:19], v24, off
	s_and_saveexec_b64 s[10:11], s[8:9]
	s_cbranch_execz .Lscan_ms_4
	global_store_dword v[22:23], v5, off
.Lscan_ms_4:
	s_or_b64 exec, exec, s[10:11]
	v_lshl_add_u64 v[18:19], v[18:19], 0, s[18:19]
	v_lshl_add_u64 v[22:23], v[22:23], 0, s[20:21]
	s_waitcnt vmcnt(38)
	v_add_f32_e32 v25, v32, v48
	v_add_f32_e32 v24, v5, v32
	v_max_f32_e32 v5, v24, v25
	v_sub_f32_e32 v25, v25, v5
	v_sub_f32_e32 v24, v24, v5
	v_mul_f32_e32 v25, 0x3fb8aa3b, v25
	v_mul_f32_e32 v24, 0x3fb8aa3b, v24
	v_exp_f32_e32 v25, v25
	v_exp_f32_e32 v24, v24
	s_nop 0
	v_mul_f32_e32 v26, v64, v25
	v_fma_f32 v20, v20, v24, v26
	v_bfe_u32 v24, v20, 16, 1
	v_add3_u32 v24, v20, v24, s73
	global_store_short_d16_hi v[18:19], v24, off
	s_and_saveexec_b64 s[10:11], s[8:9]
	s_cbranch_execz .Lscan_ms_5
	global_store_dword v[22:23], v5, off
.Lscan_ms_5:
	s_or_b64 exec, exec, s[10:11]
	v_lshl_add_u64 v[18:19], v[18:19], 0, s[18:19]
	v_lshl_add_u64 v[22:23], v[22:23], 0, s[20:21]
	s_waitcnt vmcnt(36)
	v_add_f32_e32 v25, v33, v49
	v_add_f32_e32 v24, v5, v33
	v_max_f32_e32 v5, v24, v25
	v_sub_f32_e32 v25, v25, v5
	v_sub_f32_e32 v24, v24, v5
	v_mul_f32_e32 v25, 0x3fb8aa3b, v25
	v_mul_f32_e32 v24, 0x3fb8aa3b, v24
	v_exp_f32_e32 v25, v25
	v_exp_f32_e32 v24, v24
	s_nop 0
	v_mul_f32_e32 v26, v65, v25
	v_fma_f32 v20, v20, v24, v26
	v_bfe_u32 v24, v20, 16, 1
	v_add3_u32 v24, v20, v24, s73
	global_store_short_d16_hi v[18:19], v24, off
	s_and_saveexec_b64 s[10:11], s[8:9]
	s_cbranch_execz .Lscan_ms_6
	global_store_dword v[22:23], v5, off
.Lscan_ms_6:
	s_or_b64 exec, exec, s[10:11]
	v_lshl_add_u64 v[18:19], v[18:19], 0, s[18:19]
	v_lshl_add_u64 v[22:23], v[22:23], 0, s[20:21]
	s_waitcnt vmcnt(34)
	v_add_f32_e32 v25, v34, v50
	v_add_f32_e32 v24, v5, v34
	v_max_f32_e32 v5, v24, v25
	v_sub_f32_e32 v25, v25, v5
	v_sub_f32_e32 v24, v24, v5
	v_mul_f32_e32 v25, 0x3fb8aa3b, v25
	v_mul_f32_e32 v24, 0x3fb8aa3b, v24
	v_exp_f32_e32 v25, v25
	v_exp_f32_e32 v24, v24
	s_nop 0
	v_mul_f32_e32 v26, v66, v25
	v_fma_f32 v20, v20, v24, v26
	v_bfe_u32 v24, v20, 16, 1
	v_add3_u32 v24, v20, v24, s73
	global_store_short_d16_hi v[18:19], v24, off
	s_and_saveexec_b64 s[10:11], s[8:9]
	s_cbranch_execz .Lscan_ms_7
	global_store_dword v[22:23], v5, off
.Lscan_ms_7:
	s_or_b64 exec, exec, s[10:11]
	v_lshl_add_u64 v[18:19], v[18:19], 0, s[18:19]
	v_lshl_add_u64 v[22:23], v[22:23], 0, s[20:21]
	s_waitcnt vmcnt(32)
	v_add_f32_e32 v25, v35, v51
	v_add_f32_e32 v24, v5, v35
	v_max_f32_e32 v5, v24, v25
	v_sub_f32_e32 v25, v25, v5
	v_sub_f32_e32 v24, v24, v5
	v_mul_f32_e32 v25, 0x3fb8aa3b, v25
	v_mul_f32_e32 v24, 0x3fb8aa3b, v24
	v_exp_f32_e32 v25, v25
	v_exp_f32_e32 v24, v24
	s_nop 0
	v_mul_f32_e32 v26, v67, v25
	v_fma_f32 v20, v20, v24, v26
	v_bfe_u32 v24, v20, 16, 1
	v_add3_u32 v24, v20, v24, s73
	global_store_short_d16_hi v[18:19], v24, off
	s_and_saveexec_b64 s[10:11], s[8:9]
	s_cbranch_execz .Lscan_ms_8
	global_store_dword v[22:23], v5, off
.Lscan_ms_8:
	s_or_b64 exec, exec, s[10:11]
	v_lshl_add_u64 v[18:19], v[18:19], 0, s[18:19]
	v_lshl_add_u64 v[22:23], v[22:23], 0, s[20:21]
	s_waitcnt vmcnt(30)
	v_add_f32_e32 v25, v36, v52
	v_add_f32_e32 v24, v5, v36
	v_max_f32_e32 v5, v24, v25
	v_sub_f32_e32 v25, v25, v5
	v_sub_f32_e32 v24, v24, v5
	v_mul_f32_e32 v25, 0x3fb8aa3b, v25
	v_mul_f32_e32 v24, 0x3fb8aa3b, v24
	v_exp_f32_e32 v25, v25
	v_exp_f32_e32 v24, v24
	s_nop 0
	v_mul_f32_e32 v26, v68, v25
	v_fma_f32 v20, v20, v24, v26
	v_bfe_u32 v24, v20, 16, 1
	v_add3_u32 v24, v20, v24, s73
	global_store_short_d16_hi v[18:19], v24, off
	s_and_saveexec_b64 s[10:11], s[8:9]
	s_cbranch_execz .Lscan_ms_9
	global_store_dword v[22:23], v5, off
.Lscan_ms_9:
	s_or_b64 exec, exec, s[10:11]
	v_lshl_add_u64 v[18:19], v[18:19], 0, s[18:19]
	v_lshl_add_u64 v[22:23], v[22:23], 0, s[20:21]
	s_waitcnt vmcnt(28)
	v_add_f32_e32 v25, v37, v53
	v_add_f32_e32 v24, v5, v37
	v_max_f32_e32 v5, v24, v25
	v_sub_f32_e32 v25, v25, v5
	v_sub_f32_e32 v24, v24, v5
	v_mul_f32_e32 v25, 0x3fb8aa3b, v25
	v_mul_f32_e32 v24, 0x3fb8aa3b, v24
	v_exp_f32_e32 v25, v25
	v_exp_f32_e32 v24, v24
	s_nop 0
	v_mul_f32_e32 v26, v69, v25
	v_fma_f32 v20, v20, v24, v26
	v_bfe_u32 v24, v20, 16, 1
	v_add3_u32 v24, v20, v24, s73
	global_store_short_d16_hi v[18:19], v24, off
	s_and_saveexec_b64 s[10:11], s[8:9]
	s_cbranch_execz .Lscan_ms_10
	global_store_dword v[22:23], v5, off
.Lscan_ms_10:
	s_or_b64 exec, exec, s[10:11]
	v_lshl_add_u64 v[18:19], v[18:19], 0, s[18:19]
	v_lshl_add_u64 v[22:23], v[22:23], 0, s[20:21]
	s_waitcnt vmcnt(26)
	v_add_f32_e32 v25, v38, v54
	v_add_f32_e32 v24, v5, v38
	v_max_f32_e32 v5, v24, v25
	v_sub_f32_e32 v25, v25, v5
	v_sub_f32_e32 v24, v24, v5
	v_mul_f32_e32 v25, 0x3fb8aa3b, v25
	v_mul_f32_e32 v24, 0x3fb8aa3b, v24
	v_exp_f32_e32 v25, v25
	v_exp_f32_e32 v24, v24
	s_nop 0
	v_mul_f32_e32 v26, v70, v25
	v_fma_f32 v20, v20, v24, v26
	v_bfe_u32 v24, v20, 16, 1
	v_add3_u32 v24, v20, v24, s73
	global_store_short_d16_hi v[18:19], v24, off
	s_and_saveexec_b64 s[10:11], s[8:9]
	s_cbranch_execz .Lscan_ms_11
	global_store_dword v[22:23], v5, off
.Lscan_ms_11:
	s_or_b64 exec, exec, s[10:11]
	v_lshl_add_u64 v[18:19], v[18:19], 0, s[18:19]
	v_lshl_add_u64 v[22:23], v[22:23], 0, s[20:21]
	s_waitcnt vmcnt(24)
	v_add_f32_e32 v25, v39, v55
	v_add_f32_e32 v24, v5, v39
	v_max_f32_e32 v5, v24, v25
	v_sub_f32_e32 v25, v25, v5
	v_sub_f32_e32 v24, v24, v5
	v_mul_f32_e32 v25, 0x3fb8aa3b, v25
	v_mul_f32_e32 v24, 0x3fb8aa3b, v24
	v_exp_f32_e32 v25, v25
	v_exp_f32_e32 v24, v24
	s_nop 0
	v_mul_f32_e32 v26, v71, v25
	v_fma_f32 v20, v20, v24, v26
	v_bfe_u32 v24, v20, 16, 1
	v_add3_u32 v24, v20, v24, s73
	global_store_short_d16_hi v[18:19], v24, off
	s_and_saveexec_b64 s[10:11], s[8:9]
	s_cbranch_execz .Lscan_ms_12
	global_store_dword v[22:23], v5, off
.Lscan_ms_12:
	s_or_b64 exec, exec, s[10:11]
	v_lshl_add_u64 v[18:19], v[18:19], 0, s[18:19]
	v_lshl_add_u64 v[22:23], v[22:23], 0, s[20:21]
	s_waitcnt vmcnt(22)
	v_add_f32_e32 v25, v40, v56
	v_add_f32_e32 v24, v5, v40
	v_max_f32_e32 v5, v24, v25
	v_sub_f32_e32 v25, v25, v5
	v_sub_f32_e32 v24, v24, v5
	v_mul_f32_e32 v25, 0x3fb8aa3b, v25
	v_mul_f32_e32 v24, 0x3fb8aa3b, v24
	v_exp_f32_e32 v25, v25
	v_exp_f32_e32 v24, v24
	s_nop 0
	v_mul_f32_e32 v26, v72, v25
	v_fma_f32 v20, v20, v24, v26
	v_bfe_u32 v24, v20, 16, 1
	v_add3_u32 v24, v20, v24, s73
	global_store_short_d16_hi v[18:19], v24, off
	s_and_saveexec_b64 s[10:11], s[8:9]
	s_cbranch_execz .Lscan_ms_13
	global_store_dword v[22:23], v5, off
.Lscan_ms_13:
	s_or_b64 exec, exec, s[10:11]
	v_lshl_add_u64 v[18:19], v[18:19], 0, s[18:19]
	v_lshl_add_u64 v[22:23], v[22:23], 0, s[20:21]
	s_waitcnt vmcnt(20)
	v_add_f32_e32 v25, v41, v57
	v_add_f32_e32 v24, v5, v41
	v_max_f32_e32 v5, v24, v25
	v_sub_f32_e32 v25, v25, v5
	v_sub_f32_e32 v24, v24, v5
	v_mul_f32_e32 v25, 0x3fb8aa3b, v25
	v_mul_f32_e32 v24, 0x3fb8aa3b, v24
	v_exp_f32_e32 v25, v25
	v_exp_f32_e32 v24, v24
	s_nop 0
	v_mul_f32_e32 v26, v73, v25
	v_fma_f32 v20, v20, v24, v26
	v_bfe_u32 v24, v20, 16, 1
	v_add3_u32 v24, v20, v24, s73
	global_store_short_d16_hi v[18:19], v24, off
	s_and_saveexec_b64 s[10:11], s[8:9]
	s_cbranch_execz .Lscan_ms_14
	global_store_dword v[22:23], v5, off
.Lscan_ms_14:
	s_or_b64 exec, exec, s[10:11]
	v_lshl_add_u64 v[18:19], v[18:19], 0, s[18:19]
	v_lshl_add_u64 v[22:23], v[22:23], 0, s[20:21]
	s_waitcnt vmcnt(18)
	v_add_f32_e32 v25, v42, v58
	v_add_f32_e32 v24, v5, v42
	v_max_f32_e32 v5, v24, v25
	v_sub_f32_e32 v25, v25, v5
	v_sub_f32_e32 v24, v24, v5
	v_mul_f32_e32 v25, 0x3fb8aa3b, v25
	v_mul_f32_e32 v24, 0x3fb8aa3b, v24
	v_exp_f32_e32 v25, v25
	v_exp_f32_e32 v24, v24
	s_nop 0
	v_mul_f32_e32 v26, v74, v25
	v_fma_f32 v20, v20, v24, v26
	v_bfe_u32 v24, v20, 16, 1
	v_add3_u32 v24, v20, v24, s73
	global_store_short_d16_hi v[18:19], v24, off
	s_and_saveexec_b64 s[10:11], s[8:9]
	s_cbranch_execz .Lscan_ms_15
	global_store_dword v[22:23], v5, off
.Lscan_ms_15:
	s_or_b64 exec, exec, s[10:11]
	v_lshl_add_u64 v[18:19], v[18:19], 0, s[18:19]
	v_lshl_add_u64 v[22:23], v[22:23], 0, s[20:21]
	s_waitcnt vmcnt(16)
	v_add_f32_e32 v25, v43, v59
	v_add_f32_e32 v24, v5, v43
	v_max_f32_e32 v5, v24, v25
	v_sub_f32_e32 v25, v25, v5
	v_sub_f32_e32 v24, v24, v5
	v_mul_f32_e32 v25, 0x3fb8aa3b, v25
	v_mul_f32_e32 v24, 0x3fb8aa3b, v24
	v_exp_f32_e32 v25, v25
	v_exp_f32_e32 v24, v24
	s_nop 0
	v_mul_f32_e32 v26, v75, v25
	v_fma_f32 v20, v20, v24, v26
	s_add_i32 s12, s12, -16
	s_cmp_eq_u32 s12, 0
	s_cbranch_scc0 .Lscan_loop

.LBB0_681:
	s_sub_u32 s98, s64, s74
	s_subb_u32 s99, s65, s75
	s_cmp_gt_u32 s72, 39
	s_mov_b64 s[10:11], -1
	s_cselect_b64 s[12:13], -1, 0
	s_and_b64 vcc, exec, s[14:15]
	s_cbranch_vccz .LBB0_687
	s_and_b64 vcc, exec, s[12:13]
	s_cbranch_vccz .LBB0_684
	v_add_u32_e32 v82, 0x800, v224
	v_cmp_gt_i32_e32 vcc, 8, v224
	s_mov_b64 s[10:11], 0
	s_nop 0
	v_cndmask_b32_e32 v84, -1, v82, vcc

.LBB0_689:
	v_lshlrev_b32_e32 v82, 4, v235
	v_and_b32_e32 v82, 0x1f0, v82
	v_ashrrev_i32_e32 v85, 31, v84
	v_lshl_add_u64 v[240:241], s[74:75], 0, v[82:83]
	v_lshlrev_b64 v[84:85], 12, v[84:85]
	v_lshl_add_u64 v[84:85], v[240:241], 0, v[84:85]
	v_lshl_add_u64 v[186:187], v[84:85], 0, s[98:99]
	global_load_dwordx4 v[216:219], v[186:187], off
	v_add_u32_e32 v82, 64, v235
	v_cndmask_b32_e64 v88, 0, 1, s[14:15]
	v_ashrrev_i32_e32 v89, 5, v82
	v_cmp_ne_u32_e64 s[10:11], 1, v88
	s_andn2_b64 vcc, exec, s[14:15]
	s_mov_b64 s[14:15], -1
	s_cbranch_vccnz .LBB0_695
	s_andn2_b64 vcc, exec, s[12:13]
	s_cbranch_vccnz .LBB0_692
	v_add_u32_e32 v88, 0x800, v89
	v_cmp_gt_i32_e32 vcc, 8, v89
	s_mov_b64 s[14:15], 0
	s_nop 0
	v_cndmask_b32_e32 v88, -1, v88, vcc

.LBB0_697:
	v_ashrrev_i32_e32 v89, 31, v88
	v_lshlrev_b64 v[88:89], 12, v[88:89]
	v_lshl_add_u64 v[88:89], v[240:241], 0, v[88:89]
	v_lshl_add_u64 v[186:187], v[88:89], 0, s[98:99]
	global_load_dwordx4 v[220:223], v[186:187], off
	v_add_u32_e32 v82, 0x80, v235
	v_ashrrev_i32_e32 v93, 5, v82
	s_and_b64 vcc, exec, s[10:11]
	s_mov_b64 s[14:15], -1
	s_cbranch_vccnz .LBB0_703
	s_andn2_b64 vcc, exec, s[12:13]
	s_cbranch_vccnz .LBB0_700
	v_add_u32_e32 v92, 0x800, v93
	v_cmp_gt_i32_e32 vcc, 8, v93
	s_mov_b64 s[14:15], 0
	s_nop 0
	v_cndmask_b32_e32 v92, -1, v92, vcc

.LBB0_705:
	v_ashrrev_i32_e32 v93, 31, v92
	v_lshlrev_b64 v[92:93], 12, v[92:93]
	v_lshl_add_u64 v[92:93], v[240:241], 0, v[92:93]
	v_lshl_add_u64 v[186:187], v[92:93], 0, s[98:99]
	global_load_dwordx4 v[208:211], v[186:187], off
	v_add_u32_e32 v82, 0xc0, v235
	v_ashrrev_i32_e32 v97, 5, v82
	s_and_b64 vcc, exec, s[10:11]
	s_mov_b64 s[14:15], -1
	s_cbranch_vccnz .LBB0_711
	s_andn2_b64 vcc, exec, s[12:13]
	s_cbranch_vccnz .LBB0_708
	v_add_u32_e32 v96, 0x800, v97
	v_cmp_gt_i32_e32 vcc, 8, v97
	s_mov_b64 s[14:15], 0
	s_nop 0
	v_cndmask_b32_e32 v96, -1, v96, vcc

.LBB0_713:
	v_ashrrev_i32_e32 v97, 31, v96
	v_lshlrev_b64 v[96:97], 12, v[96:97]
	v_lshl_add_u64 v[96:97], v[240:241], 0, v[96:97]
	v_lshl_add_u64 v[186:187], v[96:97], 0, s[98:99]
	global_load_dwordx4 v[212:215], v[186:187], off
	v_add_u32_e32 v82, 0x100, v235
	v_ashrrev_i32_e32 v101, 5, v82
	s_and_b64 vcc, exec, s[10:11]
	s_mov_b64 s[14:15], -1
	s_cbranch_vccnz .LBB0_719
	s_andn2_b64 vcc, exec, s[12:13]
	s_cbranch_vccnz .LBB0_716
	v_add_u32_e32 v100, 0x800, v101
	v_cmp_gt_i32_e32 vcc, 8, v101
	s_mov_b64 s[14:15], 0
	s_nop 0
	v_cndmask_b32_e32 v100, -1, v100, vcc

.LBB0_721:
	v_ashrrev_i32_e32 v101, 31, v100
	v_lshlrev_b64 v[100:101], 12, v[100:101]
	v_lshl_add_u64 v[100:101], v[240:241], 0, v[100:101]
	v_lshl_add_u64 v[186:187], v[100:101], 0, s[98:99]
	global_load_dwordx4 v[200:203], v[186:187], off
	v_add_u32_e32 v82, 0x140, v235
	v_ashrrev_i32_e32 v105, 5, v82
	s_and_b64 vcc, exec, s[10:11]
	s_mov_b64 s[14:15], -1
	s_cbranch_vccnz .LBB0_727
	s_andn2_b64 vcc, exec, s[12:13]
	s_cbranch_vccnz .LBB0_724
	v_add_u32_e32 v104, 0x800, v105
	v_cmp_gt_i32_e32 vcc, 8, v105
	s_mov_b64 s[14:15], 0
	s_nop 0
	v_cndmask_b32_e32 v104, -1, v104, vcc

.LBB0_729:
	v_ashrrev_i32_e32 v105, 31, v104
	v_lshlrev_b64 v[104:105], 12, v[104:105]
	v_lshl_add_u64 v[104:105], v[240:241], 0, v[104:105]
	v_lshl_add_u64 v[186:187], v[104:105], 0, s[98:99]
	global_load_dwordx4 v[204:207], v[186:187], off
	v_add_u32_e32 v82, 0x180, v235
	v_ashrrev_i32_e32 v113, 5, v82
	s_and_b64 vcc, exec, s[10:11]
	s_mov_b64 s[14:15], -1
	s_cbranch_vccnz .LBB0_735
	s_andn2_b64 vcc, exec, s[12:13]
	s_cbranch_vccnz .LBB0_732
	v_add_u32_e32 v112, 0x800, v113
	v_cmp_gt_i32_e32 vcc, 8, v113
	s_mov_b64 s[14:15], 0
	s_nop 0
	v_cndmask_b32_e32 v112, -1, v112, vcc

.LBB0_737:
	v_ashrrev_i32_e32 v113, 31, v112
	v_lshlrev_b64 v[112:113], 12, v[112:113]
	v_lshl_add_u64 v[112:113], v[240:241], 0, v[112:113]
	v_lshl_add_u64 v[186:187], v[112:113], 0, s[98:99]
	global_load_dwordx4 v[176:179], v[186:187], off
	v_add_u32_e32 v82, 0x1c0, v235
	v_ashrrev_i32_e32 v125, 5, v82
	s_and_b64 vcc, exec, s[10:11]
	s_mov_b64 s[14:15], -1
	s_cbranch_vccnz .LBB0_743
	s_andn2_b64 vcc, exec, s[12:13]
	s_cbranch_vccnz .LBB0_740
	v_add_u32_e32 v124, 0x800, v125
	v_cmp_gt_i32_e32 vcc, 8, v125
	s_mov_b64 s[14:15], 0
	s_nop 0
	v_cndmask_b32_e32 v124, -1, v124, vcc

.LBB0_745:
	v_ashrrev_i32_e32 v125, 31, v124
	v_lshlrev_b64 v[124:125], 12, v[124:125]
	v_lshl_add_u64 v[124:125], v[240:241], 0, v[124:125]
	v_lshl_add_u64 v[186:187], v[124:125], 0, s[98:99]
	global_load_dwordx4 v[196:199], v[186:187], off
	v_add_u32_e32 v82, 0x200, v235
	v_ashrrev_i32_e32 v137, 5, v82
	s_and_b64 vcc, exec, s[10:11]
	s_mov_b64 s[14:15], -1
	s_cbranch_vccnz .LBB0_751
	s_andn2_b64 vcc, exec, s[12:13]
	s_cbranch_vccnz .LBB0_748
	v_add_u32_e32 v136, 0x800, v137
	v_cmp_gt_i32_e32 vcc, 8, v137
	s_mov_b64 s[14:15], 0
	s_nop 0
	v_cndmask_b32_e32 v136, -1, v136, vcc

.LBB0_753:
	v_ashrrev_i32_e32 v137, 31, v136
	v_lshlrev_b64 v[136:137], 12, v[136:137]
	v_lshl_add_u64 v[136:137], v[240:241], 0, v[136:137]
	v_lshl_add_u64 v[186:187], v[136:137], 0, s[98:99]
	global_load_dwordx4 v[74:77], v[186:187], off
	v_add_u32_e32 v82, 0x240, v235
	v_ashrrev_i32_e32 v149, 5, v82
	s_and_b64 vcc, exec, s[10:11]
	s_mov_b64 s[14:15], -1
	s_cbranch_vccnz .LBB0_759
	s_andn2_b64 vcc, exec, s[12:13]
	s_cbranch_vccnz .LBB0_756
	v_add_u32_e32 v148, 0x800, v149
	v_cmp_gt_i32_e32 vcc, 8, v149
	s_mov_b64 s[14:15], 0
	s_nop 0
	v_cndmask_b32_e32 v148, -1, v148, vcc

.LBB0_761:
	v_ashrrev_i32_e32 v149, 31, v148
	v_lshlrev_b64 v[148:149], 12, v[148:149]
	v_lshl_add_u64 v[148:149], v[240:241], 0, v[148:149]
	v_lshl_add_u64 v[186:187], v[148:149], 0, s[98:99]
	global_load_dwordx4 v[78:81], v[186:187], off
	v_add_u32_e32 v82, 0x280, v235
	v_ashrrev_i32_e32 v157, 5, v82
	s_and_b64 vcc, exec, s[10:11]
	s_mov_b64 s[14:15], -1
	s_cbranch_vccnz .LBB0_767
	s_andn2_b64 vcc, exec, s[12:13]
	s_cbranch_vccnz .LBB0_764
	v_add_u32_e32 v156, 0x800, v157
	v_cmp_gt_i32_e32 vcc, 8, v157
	s_mov_b64 s[14:15], 0
	s_nop 0
	v_cndmask_b32_e32 v156, -1, v156, vcc

.LBB0_769:
	v_ashrrev_i32_e32 v157, 31, v156
	v_lshlrev_b64 v[156:157], 12, v[156:157]
	v_lshl_add_u64 v[156:157], v[240:241], 0, v[156:157]
	v_lshl_add_u64 v[186:187], v[156:157], 0, s[98:99]
	global_load_dwordx4 v[66:69], v[186:187], off
	v_add_u32_e32 v82, 0x2c0, v235
	v_ashrrev_i32_e32 v161, 5, v82
	s_and_b64 vcc, exec, s[10:11]
	s_mov_b64 s[14:15], -1
	s_cbranch_vccnz .LBB0_775
	s_andn2_b64 vcc, exec, s[12:13]
	s_cbranch_vccnz .LBB0_772
	v_add_u32_e32 v160, 0x800, v161
	v_cmp_gt_i32_e32 vcc, 8, v161
	s_mov_b64 s[14:15], 0
	s_nop 0
	v_cndmask_b32_e32 v160, -1, v160, vcc

.LBB0_777:
	v_ashrrev_i32_e32 v161, 31, v160
	v_lshlrev_b64 v[160:161], 12, v[160:161]
	v_lshl_add_u64 v[160:161], v[240:241], 0, v[160:161]
	v_lshl_add_u64 v[186:187], v[160:161], 0, s[98:99]
	global_load_dwordx4 v[70:73], v[186:187], off
	v_add_u32_e32 v82, 0x300, v235
	v_ashrrev_i32_e32 v165, 5, v82
	s_and_b64 vcc, exec, s[10:11]
	s_mov_b64 s[14:15], -1
	s_cbranch_vccnz .LBB0_783
	s_andn2_b64 vcc, exec, s[12:13]
	s_cbranch_vccnz .LBB0_780
	v_add_u32_e32 v164, 0x800, v165
	v_cmp_gt_i32_e32 vcc, 8, v165
	s_mov_b64 s[14:15], 0
	s_nop 0
	v_cndmask_b32_e32 v164, -1, v164, vcc

.LBB0_785:
	v_ashrrev_i32_e32 v165, 31, v164
	v_lshlrev_b64 v[164:165], 12, v[164:165]
	v_lshl_add_u64 v[164:165], v[240:241], 0, v[164:165]
	v_lshl_add_u64 v[186:187], v[164:165], 0, s[98:99]
	global_load_dwordx4 v[188:191], v[186:187], off
	v_add_u32_e32 v82, 0x340, v235
	v_ashrrev_i32_e32 v169, 5, v82
	s_and_b64 vcc, exec, s[10:11]
	s_mov_b64 s[14:15], -1
	s_cbranch_vccnz .LBB0_791
	s_andn2_b64 vcc, exec, s[12:13]
	s_cbranch_vccnz .LBB0_788
	v_add_u32_e32 v168, 0x800, v169
	v_cmp_gt_i32_e32 vcc, 8, v169
	s_mov_b64 s[14:15], 0
	s_nop 0
	v_cndmask_b32_e32 v168, -1, v168, vcc

.LBB0_793:
	v_ashrrev_i32_e32 v169, 31, v168
	v_lshlrev_b64 v[168:169], 12, v[168:169]
	v_lshl_add_u64 v[168:169], v[240:241], 0, v[168:169]
	v_lshl_add_u64 v[186:187], v[168:169], 0, s[98:99]
	global_load_dwordx4 v[192:195], v[186:187], off
	v_add_u32_e32 v82, 0x380, v235
	v_ashrrev_i32_e32 v173, 5, v82
	s_and_b64 vcc, exec, s[10:11]
	s_mov_b64 s[14:15], -1
	s_cbranch_vccnz .LBB0_799
	s_andn2_b64 vcc, exec, s[12:13]
	s_cbranch_vccnz .LBB0_796
	v_add_u32_e32 v172, 0x800, v173
	v_cmp_gt_i32_e32 vcc, 8, v173
	s_mov_b64 s[14:15], 0
	s_nop 0
	v_cndmask_b32_e32 v172, -1, v172, vcc

.LBB0_801:
	v_ashrrev_i32_e32 v173, 31, v172
	v_lshlrev_b64 v[172:173], 12, v[172:173]
	v_lshl_add_u64 v[172:173], v[240:241], 0, v[172:173]
	v_lshl_add_u64 v[186:187], v[172:173], 0, s[98:99]
	global_load_dwordx4 v[180:183], v[186:187], off
	v_add_u32_e32 v82, 0x3c0, v235
	v_ashrrev_i32_e32 v243, 5, v82
	s_and_b64 vcc, exec, s[10:11]
	s_mov_b64 s[10:11], -1
	s_cbranch_vccnz .LBB0_807
	s_andn2_b64 vcc, exec, s[12:13]
	s_cbranch_vccnz .LBB0_804
	v_add_u32_e32 v226, 0x800, v243
	v_cmp_gt_i32_e32 vcc, 8, v243
	s_mov_b64 s[10:11], 0
	s_nop 0
	v_cndmask_b32_e32 v242, -1, v226, vcc

.LBB0_809:
	v_ashrrev_i32_e32 v243, 31, v242
	v_lshlrev_b64 v[242:243], 12, v[242:243]
	v_lshl_add_u64 v[242:243], v[240:241], 0, v[242:243]
	v_lshl_add_u64 v[186:187], v[242:243], 0, s[98:99]
	global_load_dwordx4 v[184:187], v[186:187], off
	global_load_dwordx4 v[84:87], v[84:85], off
	global_load_dwordx4 v[88:91], v[88:89], off
	global_load_dwordx4 v[92:95], v[92:93], off
	global_load_dwordx4 v[96:99], v[96:97], off
	global_load_dwordx4 v[100:103], v[100:101], off
	global_load_dwordx4 v[104:107], v[104:105], off
	global_load_dwordx4 v[112:115], v[112:113], off
	global_load_dwordx4 v[124:127], v[124:125], off
	global_load_dwordx4 v[136:139], v[136:137], off
	global_load_dwordx4 v[148:151], v[148:149], off
	global_load_dwordx4 v[156:159], v[156:157], off
	global_load_dwordx4 v[160:163], v[160:161], off
	global_load_dwordx4 v[164:167], v[164:165], off
	global_load_dwordx4 v[168:171], v[168:169], off
	global_load_dwordx4 v[172:175], v[172:173], off
	v_mul_u32_u24_e32 v82, 0x110, v224
	v_lshl_add_u32 v82, v225, 3, v82
	v_add_u32_e32 v82, s94, v82
	v_mul_u32_u24_e32 v226, 0x110, v225
	v_lshl_add_u32 v226, v224, 4, v226
	v_add_u32_e32 v226, s94, v226
	s_waitcnt vmcnt(30)
	v_cvt_pk_bf16_f32 v216, v216, v217
	v_cvt_pk_bf16_f32 v217, v218, v219
	ds_write_b64 v82, v[216:217]
	s_waitcnt vmcnt(29)
	v_cvt_pk_bf16_f32 v220, v220, v221
	v_cvt_pk_bf16_f32 v221, v222, v223
	ds_write_b64 v82, v[220:221] offset:544
	s_waitcnt vmcnt(28)
	v_cvt_pk_bf16_f32 v208, v208, v209
	v_cvt_pk_bf16_f32 v209, v210, v211
	ds_write_b64 v82, v[208:209] offset:1088
	s_waitcnt vmcnt(27)
	v_cvt_pk_bf16_f32 v212, v212, v213
	v_cvt_pk_bf16_f32 v213, v214, v215
	ds_write_b64 v82, v[212:213] offset:1632
	s_waitcnt vmcnt(26)
	v_cvt_pk_bf16_f32 v200, v200, v201
	v_cvt_pk_bf16_f32 v201, v202, v203
	ds_write_b64 v82, v[200:201] offset:2176
	s_waitcnt vmcnt(25)
	v_cvt_pk_bf16_f32 v204, v204, v205
	v_cvt_pk_bf16_f32 v205, v206, v207
	ds_write_b64 v82, v[204:205] offset:2720
	s_waitcnt vmcnt(24)
	v_cvt_pk_bf16_f32 v176, v176, v177
	v_cvt_pk_bf16_f32 v177, v178, v179
	ds_write_b64 v82, v[176:177] offset:3264
	s_waitcnt vmcnt(23)
	v_cvt_pk_bf16_f32 v196, v196, v197
	v_cvt_pk_bf16_f32 v197, v198, v199
	ds_write_b64 v82, v[196:197] offset:3808
	s_waitcnt vmcnt(22)
	v_cvt_pk_bf16_f32 v74, v74, v75
	v_cvt_pk_bf16_f32 v75, v76, v77
	ds_write_b64 v82, v[74:75] offset:4352
	s_waitcnt vmcnt(21)
	v_cvt_pk_bf16_f32 v78, v78, v79
	v_cvt_pk_bf16_f32 v79, v80, v81
	ds_write_b64 v82, v[78:79] offset:4896
	s_waitcnt vmcnt(20)
	v_cvt_pk_bf16_f32 v66, v66, v67
	v_cvt_pk_bf16_f32 v67, v68, v69
	ds_write_b64 v82, v[66:67] offset:5440
	s_waitcnt vmcnt(19)
	v_cvt_pk_bf16_f32 v70, v70, v71
	v_cvt_pk_bf16_f32 v71, v72, v73
	ds_write_b64 v82, v[70:71] offset:5984
	s_waitcnt vmcnt(18)
	v_cvt_pk_bf16_f32 v188, v188, v189
	v_cvt_pk_bf16_f32 v189, v190, v191
	ds_write_b64 v82, v[188:189] offset:6528
	s_waitcnt vmcnt(17)
	v_cvt_pk_bf16_f32 v192, v192, v193
	v_cvt_pk_bf16_f32 v193, v194, v195
	ds_write_b64 v82, v[192:193] offset:7072
	s_waitcnt vmcnt(16)
	v_cvt_pk_bf16_f32 v180, v180, v181
	v_cvt_pk_bf16_f32 v181, v182, v183
	ds_write_b64 v82, v[180:181] offset:7616
	s_waitcnt vmcnt(15)
	v_cvt_pk_bf16_f32 v184, v184, v185
	v_cvt_pk_bf16_f32 v185, v186, v187
	ds_write_b64 v82, v[184:185] offset:8160
	global_load_dwordx4 v[176:179], v[242:243], off
	s_waitcnt lgkmcnt(0)
	ds_read_b128 v[220:223], v226
	ds_read_b128 v[212:215], v226 offset:32
	ds_read_b128 v[204:207], v226 offset:64
	ds_read_b128 v[196:199], v226 offset:96
	ds_read_b128 v[200:203], v226 offset:128
	ds_read_b128 v[208:211], v226 offset:160
	ds_read_b128 v[192:195], v226 offset:192
	ds_read_b128 v[184:187], v226 offset:224
	s_waitcnt lgkmcnt(7)
	v_mfma_f32_32x32x16_bf16 v[66:81], v[220:223], v[152:155], 0
	s_waitcnt lgkmcnt(6)
	v_mfma_f32_32x32x16_bf16 v[66:81], v[212:215], v[144:147], v[66:81]
	s_waitcnt lgkmcnt(5)
	v_mfma_f32_32x32x16_bf16 v[66:81], v[204:207], v[140:143], v[66:81]
	s_waitcnt lgkmcnt(4)
	v_mfma_f32_32x32x16_bf16 v[66:81], v[196:199], v[132:135], v[66:81]
	s_waitcnt lgkmcnt(3)
	v_mfma_f32_32x32x16_bf16 v[66:81], v[200:203], v[128:131], v[66:81]
	s_waitcnt lgkmcnt(2)
	v_mfma_f32_32x32x16_bf16 v[66:81], v[208:211], v[120:123], v[66:81]
	s_waitcnt lgkmcnt(1)
	v_mfma_f32_32x32x16_bf16 v[66:81], v[192:195], v[116:119], v[66:81]
	s_waitcnt lgkmcnt(0)
	s_mov_b64 s[10:11], 0
	v_mov_b32_e32 v180, s16
	v_mfma_f32_32x32x16_bf16 v[66:81], v[184:187], v[108:111], v[66:81]

.LBB0_1130:
	s_lshl_b32 s19, s38, 8
	v_mov_b32_e32 v132, v200
	v_mov_b32_e32 v133, v1
	s_or_b32 s19, s19, s80
	s_mov_b64 s[38:39], -1
	v_lshl_add_u32 v176, v133, 3, s19
	v_add_u32_e32 v174, s79, v132
	s_cmp_lt_i32 s36, 32
	v_ashrrev_i32_e32 v177, 31, v176
	s_mov_b64 s[58:59], 0x80000
	s_cbranch_scc0 .LBB0_1133
	v_lshlrev_b32_e32 v178, 2, v176
	v_lshl_add_u32 v179, s36, 8, v174
	v_lshl_add_u32 v179, v179, 13, v178
	global_load_dwordx4 v[132:135], v178, s[14:15]
	global_load_dwordx4 v[136:139], v178, s[14:15] offset:16
	global_load_dwordx4 v[140:143], v178, s[14:15] offset:512
	global_load_dwordx4 v[144:147], v178, s[14:15] offset:528
	global_load_dwordx4 v[148:151], v179, s[10:11]
	global_load_dwordx4 v[152:155], v179, s[10:11] offset:16
	global_load_dwordx4 v[156:159], v179, s[10:11] offset:512
	global_load_dwordx4 v[160:163], v179, s[10:11] offset:528
	v_add_u32_e32 v178, 0x20000, v179
	global_load_dwordx4 v[180:183], v178, s[10:11]
	global_load_dwordx4 v[184:187], v178, s[10:11] offset:16
	global_load_dwordx4 v[188:191], v178, s[10:11] offset:512
	global_load_dwordx4 v[192:195], v178, s[10:11] offset:528
	v_add_u32_e32 v178, 0x40000, v179
	global_load_dwordx4 v[196:199], v178, s[10:11]
	global_load_dwordx4 v[204:207], v178, s[10:11] offset:16
	global_load_dwordx4 v[208:211], v178, s[10:11] offset:512
	global_load_dwordx4 v[212:215], v178, s[10:11] offset:528
	s_waitcnt vmcnt(12)
	v_pk_add_f32 v[132:133], v[132:133], 1.0 op_sel_hi:[1,0]
	v_pk_add_f32 v[134:135], v[134:135], 1.0 op_sel_hi:[1,0]
	v_pk_add_f32 v[136:137], v[136:137], 1.0 op_sel_hi:[1,0]
	v_pk_add_f32 v[138:139], v[138:139], 1.0 op_sel_hi:[1,0]
	v_pk_add_f32 v[140:141], v[140:141], 1.0 op_sel_hi:[1,0]
	v_pk_add_f32 v[142:143], v[142:143], 1.0 op_sel_hi:[1,0]
	v_pk_add_f32 v[144:145], v[144:145], 1.0 op_sel_hi:[1,0]
	v_pk_add_f32 v[146:147], v[146:147], 1.0 op_sel_hi:[1,0]
	s_waitcnt vmcnt(8)
	v_pk_mul_f32 v[148:149], v[148:149], s[92:93] op_sel_hi:[1,0]
	v_pk_mul_f32 v[150:151], v[150:151], s[92:93] op_sel_hi:[1,0]
	v_pk_fma_f32 v[148:149], v[128:129], v[132:133], v[148:149]
	v_pk_fma_f32 v[150:151], v[130:131], v[134:135], v[150:151]
	v_pk_mul_f32 v[152:153], v[152:153], s[92:93] op_sel_hi:[1,0]
	v_pk_mul_f32 v[154:155], v[154:155], s[92:93] op_sel_hi:[1,0]
	v_pk_fma_f32 v[152:153], v[124:125], v[136:137], v[152:153]
	v_pk_fma_f32 v[154:155], v[126:127], v[138:139], v[154:155]
	v_pk_mul_f32 v[156:157], v[156:157], s[92:93] op_sel_hi:[1,0]
	v_pk_mul_f32 v[158:159], v[158:159], s[92:93] op_sel_hi:[1,0]
	v_pk_fma_f32 v[156:157], v[112:113], v[140:141], v[156:157]
	v_pk_fma_f32 v[158:159], v[114:115], v[142:143], v[158:159]
	v_pk_mul_f32 v[160:161], v[160:161], s[92:93] op_sel_hi:[1,0]
	v_pk_mul_f32 v[162:163], v[162:163], s[92:93] op_sel_hi:[1,0]
	v_pk_fma_f32 v[160:161], v[104:105], v[144:145], v[160:161]
	v_pk_fma_f32 v[162:163], v[106:107], v[146:147], v[162:163]
	v_cvt_pk_bf16_f32 v128, v148, v149
	v_cvt_pk_bf16_f32 v129, v150, v151
	v_cvt_pk_bf16_f32 v130, v152, v153
	v_cvt_pk_bf16_f32 v131, v154, v155
	v_cvt_pk_bf16_f32 v112, v156, v157
	v_cvt_pk_bf16_f32 v113, v158, v159
	v_cvt_pk_bf16_f32 v114, v160, v161
	v_cvt_pk_bf16_f32 v115, v162, v163
	v_add_u32_e32 v178, 0x60000, v179
	global_load_dwordx4 v[148:151], v178, s[10:11]
	global_load_dwordx4 v[152:155], v178, s[10:11] offset:16
	global_load_dwordx4 v[156:159], v178, s[10:11] offset:512
	global_load_dwordx4 v[160:163], v178, s[10:11] offset:528
	s_waitcnt vmcnt(8)
	v_pk_mul_f32 v[180:181], v[180:181], s[92:93] op_sel_hi:[1,0]
	v_pk_mul_f32 v[182:183], v[182:183], s[92:93] op_sel_hi:[1,0]
	v_pk_fma_f32 v[180:181], v[120:121], v[132:133], v[180:181]
	v_pk_fma_f32 v[182:183], v[122:123], v[134:135], v[182:183]
	v_pk_mul_f32 v[184:185], v[184:185], s[92:93] op_sel_hi:[1,0]
	v_pk_mul_f32 v[186:187], v[186:187], s[92:93] op_sel_hi:[1,0]
	v_pk_fma_f32 v[184:185], v[116:117], v[136:137], v[184:185]
	v_pk_fma_f32 v[186:187], v[118:119], v[138:139], v[186:187]
	v_pk_mul_f32 v[188:189], v[188:189], s[92:93] op_sel_hi:[1,0]
	v_pk_mul_f32 v[190:191], v[190:191], s[92:93] op_sel_hi:[1,0]
	v_pk_fma_f32 v[188:189], v[96:97], v[140:141], v[188:189]
	v_pk_fma_f32 v[190:191], v[98:99], v[142:143], v[190:191]
	v_pk_mul_f32 v[192:193], v[192:193], s[92:93] op_sel_hi:[1,0]
	v_pk_mul_f32 v[194:195], v[194:195], s[92:93] op_sel_hi:[1,0]
	v_pk_fma_f32 v[192:193], v[88:89], v[144:145], v[192:193]
	v_pk_fma_f32 v[194:195], v[90:91], v[146:147], v[194:195]
	v_cvt_pk_bf16_f32 v120, v180, v181
	v_cvt_pk_bf16_f32 v121, v182, v183
	v_cvt_pk_bf16_f32 v122, v184, v185
	v_cvt_pk_bf16_f32 v123, v186, v187
	v_cvt_pk_bf16_f32 v96, v188, v189
	v_cvt_pk_bf16_f32 v97, v190, v191
	v_cvt_pk_bf16_f32 v98, v192, v193
	v_cvt_pk_bf16_f32 v99, v194, v195
	v_add_u32_e32 v178, 0x100000, v179
	global_load_dwordx4 v[180:183], v178, s[10:11]
	global_load_dwordx4 v[184:187], v178, s[10:11] offset:16
	global_load_dwordx4 v[188:191], v178, s[10:11] offset:512
	global_load_dwordx4 v[192:195], v178, s[10:11] offset:528
	s_waitcnt vmcnt(8)
	v_pk_mul_f32 v[196:197], v[196:197], s[92:93] op_sel_hi:[1,0]
	v_pk_mul_f32 v[198:199], v[198:199], s[92:93] op_sel_hi:[1,0]
	v_pk_fma_f32 v[196:197], v[108:109], v[132:133], v[196:197]
	v_pk_fma_f32 v[198:199], v[110:111], v[134:135], v[198:199]
	v_pk_mul_f32 v[204:205], v[204:205], s[92:93] op_sel_hi:[1,0]
	v_pk_mul_f32 v[206:207], v[206:207], s[92:93] op_sel_hi:[1,0]
	v_pk_fma_f32 v[204:205], v[100:101], v[136:137], v[204:205]
	v_pk_fma_f32 v[206:207], v[102:103], v[138:139], v[206:207]
	v_pk_mul_f32 v[208:209], v[208:209], s[92:93] op_sel_hi:[1,0]
	v_pk_mul_f32 v[210:211], v[210:211], s[92:93] op_sel_hi:[1,0]
	v_pk_fma_f32 v[208:209], v[78:79], v[140:141], v[208:209]
	v_pk_fma_f32 v[210:211], v[80:81], v[142:143], v[210:211]
	v_pk_mul_f32 v[212:213], v[212:213], s[92:93] op_sel_hi:[1,0]
	v_pk_mul_f32 v[214:215], v[214:215], s[92:93] op_sel_hi:[1,0]
	v_pk_fma_f32 v[212:213], v[74:75], v[144:145], v[212:213]
	v_pk_fma_f32 v[214:215], v[76:77], v[146:147], v[214:215]
	v_cvt_pk_bf16_f32 v108, v196, v197
	v_cvt_pk_bf16_f32 v109, v198, v199
	v_cvt_pk_bf16_f32 v110, v204, v205
	v_cvt_pk_bf16_f32 v111, v206, v207
	v_cvt_pk_bf16_f32 v78, v208, v209
	v_cvt_pk_bf16_f32 v79, v210, v211
	v_cvt_pk_bf16_f32 v80, v212, v213
	v_cvt_pk_bf16_f32 v81, v214, v215
	v_add_u32_e32 v178, 0x120000, v179
	global_load_dwordx4 v[196:199], v178, s[10:11]
	global_load_dwordx4 v[204:207], v178, s[10:11] offset:16
	global_load_dwordx4 v[208:211], v178, s[10:11] offset:512
	global_load_dwordx4 v[212:215], v178, s[10:11] offset:528
	s_waitcnt vmcnt(8)
	v_pk_mul_f32 v[148:149], v[148:149], s[92:93] op_sel_hi:[1,0]
	v_pk_mul_f32 v[150:151], v[150:151], s[92:93] op_sel_hi:[1,0]
	v_pk_fma_f32 v[148:149], v[92:93], v[132:133], v[148:149]
	v_pk_fma_f32 v[150:151], v[94:95], v[134:135], v[150:151]
	v_pk_mul_f32 v[152:153], v[152:153], s[92:93] op_sel_hi:[1,0]
	v_pk_mul_f32 v[154:155], v[154:155], s[92:93] op_sel_hi:[1,0]
	v_pk_fma_f32 v[152:153], v[84:85], v[136:137], v[152:153]
	v_pk_fma_f32 v[154:155], v[86:87], v[138:139], v[154:155]
	v_pk_mul_f32 v[156:157], v[156:157], s[92:93] op_sel_hi:[1,0]
	v_pk_mul_f32 v[158:159], v[158:159], s[92:93] op_sel_hi:[1,0]
	v_pk_fma_f32 v[156:157], v[70:71], v[140:141], v[156:157]
	v_pk_fma_f32 v[158:159], v[72:73], v[142:143], v[158:159]
	v_pk_mul_f32 v[160:161], v[160:161], s[92:93] op_sel_hi:[1,0]
	v_pk_mul_f32 v[162:163], v[162:163], s[92:93] op_sel_hi:[1,0]
	v_pk_fma_f32 v[160:161], v[66:67], v[144:145], v[160:161]
	v_pk_fma_f32 v[162:163], v[68:69], v[146:147], v[162:163]
	v_cvt_pk_bf16_f32 v92, v148, v149
	v_cvt_pk_bf16_f32 v93, v150, v151
	v_cvt_pk_bf16_f32 v94, v152, v153
	v_cvt_pk_bf16_f32 v95, v154, v155
	v_cvt_pk_bf16_f32 v70, v156, v157
	v_cvt_pk_bf16_f32 v71, v158, v159
	v_cvt_pk_bf16_f32 v72, v160, v161
	v_cvt_pk_bf16_f32 v73, v162, v163
	v_add_u32_e32 v178, 0x140000, v179
	global_load_dwordx4 v[148:151], v178, s[10:11]
	global_load_dwordx4 v[152:155], v178, s[10:11] offset:16
	global_load_dwordx4 v[156:159], v178, s[10:11] offset:512
	global_load_dwordx4 v[160:163], v178, s[10:11] offset:528
	s_waitcnt vmcnt(8)
	v_pk_mul_f32 v[180:181], v[180:181], s[92:93] op_sel_hi:[1,0]
	v_pk_mul_f32 v[182:183], v[182:183], s[92:93] op_sel_hi:[1,0]
	v_pk_fma_f32 v[180:181], v[62:63], v[132:133], v[180:181]
	v_pk_fma_f32 v[182:183], v[64:65], v[134:135], v[182:183]
	v_pk_mul_f32 v[184:185], v[184:185], s[92:93] op_sel_hi:[1,0]
	v_pk_mul_f32 v[186:187], v[186:187], s[92:93] op_sel_hi:[1,0]
	v_pk_fma_f32 v[184:185], v[58:59], v[136:137], v[184:185]
	v_pk_fma_f32 v[186:187], v[60:61], v[138:139], v[186:187]
	v_pk_mul_f32 v[188:189], v[188:189], s[92:93] op_sel_hi:[1,0]
	v_pk_mul_f32 v[190:191], v[190:191], s[92:93] op_sel_hi:[1,0]
	v_pk_fma_f32 v[188:189], v[46:47], v[140:141], v[188:189]
	v_pk_fma_f32 v[190:191], v[48:49], v[142:143], v[190:191]
	v_pk_mul_f32 v[192:193], v[192:193], s[92:93] op_sel_hi:[1,0]
	v_pk_mul_f32 v[194:195], v[194:195], s[92:93] op_sel_hi:[1,0]
	v_pk_fma_f32 v[192:193], v[42:43], v[144:145], v[192:193]
	v_pk_fma_f32 v[194:195], v[44:45], v[146:147], v[194:195]
	v_cvt_pk_bf16_f32 v62, v180, v181
	v_cvt_pk_bf16_f32 v63, v182, v183
	v_cvt_pk_bf16_f32 v64, v184, v185
	v_cvt_pk_bf16_f32 v65, v186, v187
	v_cvt_pk_bf16_f32 v46, v188, v189
	v_cvt_pk_bf16_f32 v47, v190, v191
	v_cvt_pk_bf16_f32 v48, v192, v193
	v_cvt_pk_bf16_f32 v49, v194, v195
	v_add_u32_e32 v178, 0x160000, v179
	global_load_dwordx4 v[180:183], v178, s[10:11]
	global_load_dwordx4 v[184:187], v178, s[10:11] offset:16
	global_load_dwordx4 v[188:191], v178, s[10:11] offset:512
	global_load_dwordx4 v[192:195], v178, s[10:11] offset:528
	s_waitcnt vmcnt(8)
	v_pk_mul_f32 v[196:197], v[196:197], s[92:93] op_sel_hi:[1,0]
	v_pk_mul_f32 v[198:199], v[198:199], s[92:93] op_sel_hi:[1,0]
	v_pk_fma_f32 v[196:197], v[54:55], v[132:133], v[196:197]
	v_pk_fma_f32 v[198:199], v[56:57], v[134:135], v[198:199]
	v_pk_mul_f32 v[204:205], v[204:205], s[92:93] op_sel_hi:[1,0]
	v_pk_mul_f32 v[206:207], v[206:207], s[92:93] op_sel_hi:[1,0]
	v_pk_fma_f32 v[204:205], v[50:51], v[136:137], v[204:205]
	v_pk_fma_f32 v[206:207], v[52:53], v[138:139], v[206:207]
	v_pk_mul_f32 v[208:209], v[208:209], s[92:93] op_sel_hi:[1,0]
	v_pk_mul_f32 v[210:211], v[210:211], s[92:93] op_sel_hi:[1,0]
	v_pk_fma_f32 v[208:209], v[30:31], v[140:141], v[208:209]
	v_pk_fma_f32 v[210:211], v[32:33], v[142:143], v[210:211]
	v_pk_mul_f32 v[212:213], v[212:213], s[92:93] op_sel_hi:[1,0]
	v_pk_mul_f32 v[214:215], v[214:215], s[92:93] op_sel_hi:[1,0]
	v_pk_fma_f32 v[212:213], v[26:27], v[144:145], v[212:213]
	v_pk_fma_f32 v[214:215], v[28:29], v[146:147], v[214:215]
	v_cvt_pk_bf16_f32 v54, v196, v197
	v_cvt_pk_bf16_f32 v55, v198, v199
	v_cvt_pk_bf16_f32 v56, v204, v205
	v_cvt_pk_bf16_f32 v57, v206, v207
	v_cvt_pk_bf16_f32 v30, v208, v209
	v_cvt_pk_bf16_f32 v31, v210, v211
	v_cvt_pk_bf16_f32 v32, v212, v213
	v_cvt_pk_bf16_f32 v33, v214, v215
	s_waitcnt vmcnt(4)
	v_pk_mul_f32 v[148:149], v[148:149], s[92:93] op_sel_hi:[1,0]
	v_pk_mul_f32 v[150:151], v[150:151], s[92:93] op_sel_hi:[1,0]
	v_pk_fma_f32 v[148:149], v[38:39], v[132:133], v[148:149]
	v_pk_fma_f32 v[150:151], v[40:41], v[134:135], v[150:151]
	v_pk_mul_f32 v[152:153], v[152:153], s[92:93] op_sel_hi:[1,0]
	v_pk_mul_f32 v[154:155], v[154:155], s[92:93] op_sel_hi:[1,0]
	v_pk_fma_f32 v[152:153], v[34:35], v[136:137], v[152:153]
	v_pk_fma_f32 v[154:155], v[36:37], v[138:139], v[154:155]
	v_pk_mul_f32 v[156:157], v[156:157], s[92:93] op_sel_hi:[1,0]
	v_pk_mul_f32 v[158:159], v[158:159], s[92:93] op_sel_hi:[1,0]
	v_pk_fma_f32 v[156:157], v[14:15], v[140:141], v[156:157]
	v_pk_fma_f32 v[158:159], v[16:17], v[142:143], v[158:159]
	v_pk_mul_f32 v[160:161], v[160:161], s[92:93] op_sel_hi:[1,0]
	v_pk_mul_f32 v[162:163], v[162:163], s[92:93] op_sel_hi:[1,0]
	v_pk_fma_f32 v[160:161], v[10:11], v[144:145], v[160:161]
	v_pk_fma_f32 v[162:163], v[12:13], v[146:147], v[162:163]
	v_cvt_pk_bf16_f32 v38, v148, v149
	v_cvt_pk_bf16_f32 v39, v150, v151
	v_cvt_pk_bf16_f32 v40, v152, v153
	v_cvt_pk_bf16_f32 v41, v154, v155
	v_cvt_pk_bf16_f32 v14, v156, v157
	v_cvt_pk_bf16_f32 v15, v158, v159
	v_cvt_pk_bf16_f32 v16, v160, v161
	v_cvt_pk_bf16_f32 v17, v162, v163
	s_waitcnt vmcnt(0)
	v_pk_mul_f32 v[180:181], v[180:181], s[92:93] op_sel_hi:[1,0]
	v_pk_mul_f32 v[182:183], v[182:183], s[92:93] op_sel_hi:[1,0]
	v_pk_fma_f32 v[180:181], v[22:23], v[132:133], v[180:181]
	v_pk_fma_f32 v[182:183], v[24:25], v[134:135], v[182:183]
	v_pk_mul_f32 v[184:185], v[184:185], s[92:93] op_sel_hi:[1,0]
	v_pk_mul_f32 v[186:187], v[186:187], s[92:93] op_sel_hi:[1,0]
	v_pk_fma_f32 v[184:185], v[18:19], v[136:137], v[184:185]
	v_pk_fma_f32 v[186:187], v[20:21], v[138:139], v[186:187]
	v_pk_mul_f32 v[188:189], v[188:189], s[92:93] op_sel_hi:[1,0]
	v_pk_mul_f32 v[190:191], v[190:191], s[92:93] op_sel_hi:[1,0]
	v_pk_fma_f32 v[188:189], v[6:7], v[140:141], v[188:189]
	v_pk_fma_f32 v[190:191], v[8:9], v[142:143], v[190:191]
	v_pk_mul_f32 v[192:193], v[192:193], s[92:93] op_sel_hi:[1,0]
	v_pk_mul_f32 v[194:195], v[194:195], s[92:93] op_sel_hi:[1,0]
	v_pk_fma_f32 v[192:193], v[2:3], v[144:145], v[192:193]
	v_pk_fma_f32 v[194:195], v[4:5], v[146:147], v[194:195]
	v_cvt_pk_bf16_f32 v22, v180, v181
	v_cvt_pk_bf16_f32 v23, v182, v183
	v_cvt_pk_bf16_f32 v24, v184, v185
	v_cvt_pk_bf16_f32 v25, v186, v187
	v_cvt_pk_bf16_f32 v6, v188, v189
	v_cvt_pk_bf16_f32 v7, v190, v191
	v_cvt_pk_bf16_f32 v8, v192, v193
	v_cvt_pk_bf16_f32 v9, v194, v195
	v_lshrrev_b32_e32 v179, 1, v179
	global_store_dwordx4 v179, v[128:131], s[12:13]
	global_store_dwordx4 v179, v[112:115], s[12:13] offset:256
	v_add_u32_e32 v178, 0x10000, v179
	global_store_dwordx4 v178, v[120:123], s[12:13]
	global_store_dwordx4 v178, v[96:99], s[12:13] offset:256
	v_add_u32_e32 v178, 0x20000, v179
	global_store_dwordx4 v178, v[108:111], s[12:13]
	global_store_dwordx4 v178, v[78:81], s[12:13] offset:256
	v_add_u32_e32 v178, 0x30000, v179
	global_store_dwordx4 v178, v[92:95], s[12:13]
	global_store_dwordx4 v178, v[70:73], s[12:13] offset:256
	v_add_u32_e32 v178, 0x80000, v179
	global_store_dwordx4 v178, v[62:65], s[12:13]
	global_store_dwordx4 v178, v[46:49], s[12:13] offset:256
	v_add_u32_e32 v178, 0x90000, v179
	global_store_dwordx4 v178, v[54:57], s[12:13]
	global_store_dwordx4 v178, v[30:33], s[12:13] offset:256
	v_add_u32_e32 v178, 0xa0000, v179
	global_store_dwordx4 v178, v[38:41], s[12:13]
	global_store_dwordx4 v178, v[14:17], s[12:13] offset:256
	v_add_u32_e32 v178, 0xb0000, v179
	global_store_dwordx4 v178, v[22:25], s[12:13]
	global_store_dwordx4 v178, v[6:9], s[12:13] offset:256
	s_nop 1
	s_cbranch_execz .LBB0_1134

.LBB0_1621:
	s_lshl_b32 s34, s86, 8
	v_mov_b32_e32 v132, v1
	v_mov_b32_e32 v133, v200
	s_or_b32 s34, s34, s72
	s_cmp_lt_i32 s21, 32
	v_lshl_add_u32 v176, v132, 3, s34
	v_add_u32_e32 v174, s65, v133
	s_mov_b64 s[34:35], -1
	v_ashrrev_i32_e32 v177, 31, v176
	s_cbranch_scc0 .LBB0_1624
	v_lshlrev_b32_e32 v178, 2, v176
	v_lshl_add_u32 v179, s21, 8, v174
	v_lshl_add_u32 v179, v179, 13, v178
	global_load_dwordx4 v[132:135], v178, s[16:17]
	global_load_dwordx4 v[136:139], v178, s[16:17] offset:16
	global_load_dwordx4 v[140:143], v178, s[16:17] offset:512
	global_load_dwordx4 v[144:147], v178, s[16:17] offset:528
	global_load_dwordx4 v[148:151], v179, s[14:15]
	global_load_dwordx4 v[152:155], v179, s[14:15] offset:16
	global_load_dwordx4 v[156:159], v179, s[14:15] offset:512
	global_load_dwordx4 v[160:163], v179, s[14:15] offset:528
	v_add_u32_e32 v178, 0x20000, v179
	global_load_dwordx4 v[180:183], v178, s[14:15]
	global_load_dwordx4 v[184:187], v178, s[14:15] offset:16
	global_load_dwordx4 v[188:191], v178, s[14:15] offset:512
	global_load_dwordx4 v[192:195], v178, s[14:15] offset:528
	v_add_u32_e32 v178, 0x40000, v179
	global_load_dwordx4 v[196:199], v178, s[14:15]
	global_load_dwordx4 v[204:207], v178, s[14:15] offset:16
	global_load_dwordx4 v[208:211], v178, s[14:15] offset:512
	global_load_dwordx4 v[212:215], v178, s[14:15] offset:528
	s_waitcnt vmcnt(12)
	v_pk_add_f32 v[132:133], v[132:133], 1.0 op_sel_hi:[1,0]
	v_pk_add_f32 v[134:135], v[134:135], 1.0 op_sel_hi:[1,0]
	v_pk_add_f32 v[136:137], v[136:137], 1.0 op_sel_hi:[1,0]
	v_pk_add_f32 v[138:139], v[138:139], 1.0 op_sel_hi:[1,0]
	v_pk_add_f32 v[140:141], v[140:141], 1.0 op_sel_hi:[1,0]
	v_pk_add_f32 v[142:143], v[142:143], 1.0 op_sel_hi:[1,0]
	v_pk_add_f32 v[144:145], v[144:145], 1.0 op_sel_hi:[1,0]
	v_pk_add_f32 v[146:147], v[146:147], 1.0 op_sel_hi:[1,0]
	s_waitcnt vmcnt(8)
	v_pk_mul_f32 v[148:149], v[148:149], s[92:93] op_sel_hi:[1,0]
	v_pk_mul_f32 v[150:151], v[150:151], s[92:93] op_sel_hi:[1,0]
	v_pk_fma_f32 v[148:149], v[128:129], v[132:133], v[148:149]
	v_pk_fma_f32 v[150:151], v[130:131], v[134:135], v[150:151]
	v_pk_mul_f32 v[152:153], v[152:153], s[92:93] op_sel_hi:[1,0]
	v_pk_mul_f32 v[154:155], v[154:155], s[92:93] op_sel_hi:[1,0]
	v_pk_fma_f32 v[152:153], v[124:125], v[136:137], v[152:153]
	v_pk_fma_f32 v[154:155], v[126:127], v[138:139], v[154:155]
	v_pk_mul_f32 v[156:157], v[156:157], s[92:93] op_sel_hi:[1,0]
	v_pk_mul_f32 v[158:159], v[158:159], s[92:93] op_sel_hi:[1,0]
	v_pk_fma_f32 v[156:157], v[112:113], v[140:141], v[156:157]
	v_pk_fma_f32 v[158:159], v[114:115], v[142:143], v[158:159]
	v_pk_mul_f32 v[160:161], v[160:161], s[92:93] op_sel_hi:[1,0]
	v_pk_mul_f32 v[162:163], v[162:163], s[92:93] op_sel_hi:[1,0]
	v_pk_fma_f32 v[160:161], v[104:105], v[144:145], v[160:161]
	v_pk_fma_f32 v[162:163], v[106:107], v[146:147], v[162:163]
	v_cvt_pk_bf16_f32 v128, v148, v149
	v_cvt_pk_bf16_f32 v129, v150, v151
	v_cvt_pk_bf16_f32 v130, v152, v153
	v_cvt_pk_bf16_f32 v131, v154, v155
	v_cvt_pk_bf16_f32 v112, v156, v157
	v_cvt_pk_bf16_f32 v113, v158, v159
	v_cvt_pk_bf16_f32 v114, v160, v161
	v_cvt_pk_bf16_f32 v115, v162, v163
	v_add_u32_e32 v178, 0x60000, v179
	global_load_dwordx4 v[148:151], v178, s[14:15]
	global_load_dwordx4 v[152:155], v178, s[14:15] offset:16
	global_load_dwordx4 v[156:159], v178, s[14:15] offset:512
	global_load_dwordx4 v[160:163], v178, s[14:15] offset:528
	s_waitcnt vmcnt(8)
	v_pk_mul_f32 v[180:181], v[180:181], s[92:93] op_sel_hi:[1,0]
	v_pk_mul_f32 v[182:183], v[182:183], s[92:93] op_sel_hi:[1,0]
	v_pk_fma_f32 v[180:181], v[120:121], v[132:133], v[180:181]
	v_pk_fma_f32 v[182:183], v[122:123], v[134:135], v[182:183]
	v_pk_mul_f32 v[184:185], v[184:185], s[92:93] op_sel_hi:[1,0]
	v_pk_mul_f32 v[186:187], v[186:187], s[92:93] op_sel_hi:[1,0]
	v_pk_fma_f32 v[184:185], v[116:117], v[136:137], v[184:185]
	v_pk_fma_f32 v[186:187], v[118:119], v[138:139], v[186:187]
	v_pk_mul_f32 v[188:189], v[188:189], s[92:93] op_sel_hi:[1,0]
	v_pk_mul_f32 v[190:191], v[190:191], s[92:93] op_sel_hi:[1,0]
	v_pk_fma_f32 v[188:189], v[96:97], v[140:141], v[188:189]
	v_pk_fma_f32 v[190:191], v[98:99], v[142:143], v[190:191]
	v_pk_mul_f32 v[192:193], v[192:193], s[92:93] op_sel_hi:[1,0]
	v_pk_mul_f32 v[194:195], v[194:195], s[92:93] op_sel_hi:[1,0]
	v_pk_fma_f32 v[192:193], v[88:89], v[144:145], v[192:193]
	v_pk_fma_f32 v[194:195], v[90:91], v[146:147], v[194:195]
	v_cvt_pk_bf16_f32 v120, v180, v181
	v_cvt_pk_bf16_f32 v121, v182, v183
	v_cvt_pk_bf16_f32 v122, v184, v185
	v_cvt_pk_bf16_f32 v123, v186, v187
	v_cvt_pk_bf16_f32 v96, v188, v189
	v_cvt_pk_bf16_f32 v97, v190, v191
	v_cvt_pk_bf16_f32 v98, v192, v193
	v_cvt_pk_bf16_f32 v99, v194, v195
	v_add_u32_e32 v178, 0x100000, v179
	global_load_dwordx4 v[180:183], v178, s[14:15]
	global_load_dwordx4 v[184:187], v178, s[14:15] offset:16
	global_load_dwordx4 v[188:191], v178, s[14:15] offset:512
	global_load_dwordx4 v[192:195], v178, s[14:15] offset:528
	s_waitcnt vmcnt(8)
	v_pk_mul_f32 v[196:197], v[196:197], s[92:93] op_sel_hi:[1,0]
	v_pk_mul_f32 v[198:199], v[198:199], s[92:93] op_sel_hi:[1,0]
	v_pk_fma_f32 v[196:197], v[108:109], v[132:133], v[196:197]
	v_pk_fma_f32 v[198:199], v[110:111], v[134:135], v[198:199]
	v_pk_mul_f32 v[204:205], v[204:205], s[92:93] op_sel_hi:[1,0]
	v_pk_mul_f32 v[206:207], v[206:207], s[92:93] op_sel_hi:[1,0]
	v_pk_fma_f32 v[204:205], v[100:101], v[136:137], v[204:205]
	v_pk_fma_f32 v[206:207], v[102:103], v[138:139], v[206:207]
	v_pk_mul_f32 v[208:209], v[208:209], s[92:93] op_sel_hi:[1,0]
	v_pk_mul_f32 v[210:211], v[210:211], s[92:93] op_sel_hi:[1,0]
	v_pk_fma_f32 v[208:209], v[78:79], v[140:141], v[208:209]
	v_pk_fma_f32 v[210:211], v[80:81], v[142:143], v[210:211]
	v_pk_mul_f32 v[212:213], v[212:213], s[92:93] op_sel_hi:[1,0]
	v_pk_mul_f32 v[214:215], v[214:215], s[92:93] op_sel_hi:[1,0]
	v_pk_fma_f32 v[212:213], v[74:75], v[144:145], v[212:213]
	v_pk_fma_f32 v[214:215], v[76:77], v[146:147], v[214:215]
	v_cvt_pk_bf16_f32 v108, v196, v197
	v_cvt_pk_bf16_f32 v109, v198, v199
	v_cvt_pk_bf16_f32 v110, v204, v205
	v_cvt_pk_bf16_f32 v111, v206, v207
	v_cvt_pk_bf16_f32 v78, v208, v209
	v_cvt_pk_bf16_f32 v79, v210, v211
	v_cvt_pk_bf16_f32 v80, v212, v213
	v_cvt_pk_bf16_f32 v81, v214, v215
	v_add_u32_e32 v178, 0x120000, v179
	global_load_dwordx4 v[196:199], v178, s[14:15]
	global_load_dwordx4 v[204:207], v178, s[14:15] offset:16
	global_load_dwordx4 v[208:211], v178, s[14:15] offset:512
	global_load_dwordx4 v[212:215], v178, s[14:15] offset:528
	s_waitcnt vmcnt(8)
	v_pk_mul_f32 v[148:149], v[148:149], s[92:93] op_sel_hi:[1,0]
	v_pk_mul_f32 v[150:151], v[150:151], s[92:93] op_sel_hi:[1,0]
	v_pk_fma_f32 v[148:149], v[92:93], v[132:133], v[148:149]
	v_pk_fma_f32 v[150:151], v[94:95], v[134:135], v[150:151]
	v_pk_mul_f32 v[152:153], v[152:153], s[92:93] op_sel_hi:[1,0]
	v_pk_mul_f32 v[154:155], v[154:155], s[92:93] op_sel_hi:[1,0]
	v_pk_fma_f32 v[152:153], v[84:85], v[136:137], v[152:153]
	v_pk_fma_f32 v[154:155], v[86:87], v[138:139], v[154:155]
	v_pk_mul_f32 v[156:157], v[156:157], s[92:93] op_sel_hi:[1,0]
	v_pk_mul_f32 v[158:159], v[158:159], s[92:93] op_sel_hi:[1,0]
	v_pk_fma_f32 v[156:157], v[70:71], v[140:141], v[156:157]
	v_pk_fma_f32 v[158:159], v[72:73], v[142:143], v[158:159]
	v_pk_mul_f32 v[160:161], v[160:161], s[92:93] op_sel_hi:[1,0]
	v_pk_mul_f32 v[162:163], v[162:163], s[92:93] op_sel_hi:[1,0]
	v_pk_fma_f32 v[160:161], v[66:67], v[144:145], v[160:161]
	v_pk_fma_f32 v[162:163], v[68:69], v[146:147], v[162:163]
	v_cvt_pk_bf16_f32 v92, v148, v149
	v_cvt_pk_bf16_f32 v93, v150, v151
	v_cvt_pk_bf16_f32 v94, v152, v153
	v_cvt_pk_bf16_f32 v95, v154, v155
	v_cvt_pk_bf16_f32 v70, v156, v157
	v_cvt_pk_bf16_f32 v71, v158, v159
	v_cvt_pk_bf16_f32 v72, v160, v161
	v_cvt_pk_bf16_f32 v73, v162, v163
	v_add_u32_e32 v178, 0x140000, v179
	global_load_dwordx4 v[148:151], v178, s[14:15]
	global_load_dwordx4 v[152:155], v178, s[14:15] offset:16
	global_load_dwordx4 v[156:159], v178, s[14:15] offset:512
	global_load_dwordx4 v[160:163], v178, s[14:15] offset:528
	s_waitcnt vmcnt(8)
	v_pk_mul_f32 v[180:181], v[180:181], s[92:93] op_sel_hi:[1,0]
	v_pk_mul_f32 v[182:183], v[182:183], s[92:93] op_sel_hi:[1,0]
	v_pk_fma_f32 v[180:181], v[62:63], v[132:133], v[180:181]
	v_pk_fma_f32 v[182:183], v[64:65], v[134:135], v[182:183]
	v_pk_mul_f32 v[184:185], v[184:185], s[92:93] op_sel_hi:[1,0]
	v_pk_mul_f32 v[186:187], v[186:187], s[92:93] op_sel_hi:[1,0]
	v_pk_fma_f32 v[184:185], v[58:59], v[136:137], v[184:185]
	v_pk_fma_f32 v[186:187], v[60:61], v[138:139], v[186:187]
	v_pk_mul_f32 v[188:189], v[188:189], s[92:93] op_sel_hi:[1,0]
	v_pk_mul_f32 v[190:191], v[190:191], s[92:93] op_sel_hi:[1,0]
	v_pk_fma_f32 v[188:189], v[46:47], v[140:141], v[188:189]
	v_pk_fma_f32 v[190:191], v[48:49], v[142:143], v[190:191]
	v_pk_mul_f32 v[192:193], v[192:193], s[92:93] op_sel_hi:[1,0]
	v_pk_mul_f32 v[194:195], v[194:195], s[92:93] op_sel_hi:[1,0]
	v_pk_fma_f32 v[192:193], v[42:43], v[144:145], v[192:193]
	v_pk_fma_f32 v[194:195], v[44:45], v[146:147], v[194:195]
	v_cvt_pk_bf16_f32 v62, v180, v181
	v_cvt_pk_bf16_f32 v63, v182, v183
	v_cvt_pk_bf16_f32 v64, v184, v185
	v_cvt_pk_bf16_f32 v65, v186, v187
	v_cvt_pk_bf16_f32 v46, v188, v189
	v_cvt_pk_bf16_f32 v47, v190, v191
	v_cvt_pk_bf16_f32 v48, v192, v193
	v_cvt_pk_bf16_f32 v49, v194, v195
	v_add_u32_e32 v178, 0x160000, v179
	global_load_dwordx4 v[180:183], v178, s[14:15]
	global_load_dwordx4 v[184:187], v178, s[14:15] offset:16
	global_load_dwordx4 v[188:191], v178, s[14:15] offset:512
	global_load_dwordx4 v[192:195], v178, s[14:15] offset:528
	s_waitcnt vmcnt(8)
	v_pk_mul_f32 v[196:197], v[196:197], s[92:93] op_sel_hi:[1,0]
	v_pk_mul_f32 v[198:199], v[198:199], s[92:93] op_sel_hi:[1,0]
	v_pk_fma_f32 v[196:197], v[54:55], v[132:133], v[196:197]
	v_pk_fma_f32 v[198:199], v[56:57], v[134:135], v[198:199]
	v_pk_mul_f32 v[204:205], v[204:205], s[92:93] op_sel_hi:[1,0]
	v_pk_mul_f32 v[206:207], v[206:207], s[92:93] op_sel_hi:[1,0]
	v_pk_fma_f32 v[204:205], v[50:51], v[136:137], v[204:205]
	v_pk_fma_f32 v[206:207], v[52:53], v[138:139], v[206:207]
	v_pk_mul_f32 v[208:209], v[208:209], s[92:93] op_sel_hi:[1,0]
	v_pk_mul_f32 v[210:211], v[210:211], s[92:93] op_sel_hi:[1,0]
	v_pk_fma_f32 v[208:209], v[30:31], v[140:141], v[208:209]
	v_pk_fma_f32 v[210:211], v[32:33], v[142:143], v[210:211]
	v_pk_mul_f32 v[212:213], v[212:213], s[92:93] op_sel_hi:[1,0]
	v_pk_mul_f32 v[214:215], v[214:215], s[92:93] op_sel_hi:[1,0]
	v_pk_fma_f32 v[212:213], v[26:27], v[144:145], v[212:213]
	v_pk_fma_f32 v[214:215], v[28:29], v[146:147], v[214:215]
	v_cvt_pk_bf16_f32 v54, v196, v197
	v_cvt_pk_bf16_f32 v55, v198, v199
	v_cvt_pk_bf16_f32 v56, v204, v205
	v_cvt_pk_bf16_f32 v57, v206, v207
	v_cvt_pk_bf16_f32 v30, v208, v209
	v_cvt_pk_bf16_f32 v31, v210, v211
	v_cvt_pk_bf16_f32 v32, v212, v213
	v_cvt_pk_bf16_f32 v33, v214, v215
	s_waitcnt vmcnt(4)
	v_pk_mul_f32 v[148:149], v[148:149], s[92:93] op_sel_hi:[1,0]
	v_pk_mul_f32 v[150:151], v[150:151], s[92:93] op_sel_hi:[1,0]
	v_pk_fma_f32 v[148:149], v[38:39], v[132:133], v[148:149]
	v_pk_fma_f32 v[150:151], v[40:41], v[134:135], v[150:151]
	v_pk_mul_f32 v[152:153], v[152:153], s[92:93] op_sel_hi:[1,0]
	v_pk_mul_f32 v[154:155], v[154:155], s[92:93] op_sel_hi:[1,0]
	v_pk_fma_f32 v[152:153], v[34:35], v[136:137], v[152:153]
	v_pk_fma_f32 v[154:155], v[36:37], v[138:139], v[154:155]
	v_pk_mul_f32 v[156:157], v[156:157], s[92:93] op_sel_hi:[1,0]
	v_pk_mul_f32 v[158:159], v[158:159], s[92:93] op_sel_hi:[1,0]
	v_pk_fma_f32 v[156:157], v[14:15], v[140:141], v[156:157]
	v_pk_fma_f32 v[158:159], v[16:17], v[142:143], v[158:159]
	v_pk_mul_f32 v[160:161], v[160:161], s[92:93] op_sel_hi:[1,0]
	v_pk_mul_f32 v[162:163], v[162:163], s[92:93] op_sel_hi:[1,0]
	v_pk_fma_f32 v[160:161], v[10:11], v[144:145], v[160:161]
	v_pk_fma_f32 v[162:163], v[12:13], v[146:147], v[162:163]
	v_cvt_pk_bf16_f32 v38, v148, v149
	v_cvt_pk_bf16_f32 v39, v150, v151
	v_cvt_pk_bf16_f32 v40, v152, v153
	v_cvt_pk_bf16_f32 v41, v154, v155
	v_cvt_pk_bf16_f32 v14, v156, v157
	v_cvt_pk_bf16_f32 v15, v158, v159
	v_cvt_pk_bf16_f32 v16, v160, v161
	v_cvt_pk_bf16_f32 v17, v162, v163
	s_waitcnt vmcnt(0)
	v_pk_mul_f32 v[180:181], v[180:181], s[92:93] op_sel_hi:[1,0]
	v_pk_mul_f32 v[182:183], v[182:183], s[92:93] op_sel_hi:[1,0]
	v_pk_fma_f32 v[180:181], v[22:23], v[132:133], v[180:181]
	v_pk_fma_f32 v[182:183], v[24:25], v[134:135], v[182:183]
	v_pk_mul_f32 v[184:185], v[184:185], s[92:93] op_sel_hi:[1,0]
	v_pk_mul_f32 v[186:187], v[186:187], s[92:93] op_sel_hi:[1,0]
	v_pk_fma_f32 v[184:185], v[18:19], v[136:137], v[184:185]
	v_pk_fma_f32 v[186:187], v[20:21], v[138:139], v[186:187]
	v_pk_mul_f32 v[188:189], v[188:189], s[92:93] op_sel_hi:[1,0]
	v_pk_mul_f32 v[190:191], v[190:191], s[92:93] op_sel_hi:[1,0]
	v_pk_fma_f32 v[188:189], v[6:7], v[140:141], v[188:189]
	v_pk_fma_f32 v[190:191], v[8:9], v[142:143], v[190:191]
	v_pk_mul_f32 v[192:193], v[192:193], s[92:93] op_sel_hi:[1,0]
	v_pk_mul_f32 v[194:195], v[194:195], s[92:93] op_sel_hi:[1,0]
	v_pk_fma_f32 v[192:193], v[2:3], v[144:145], v[192:193]
	v_pk_fma_f32 v[194:195], v[4:5], v[146:147], v[194:195]
	v_cvt_pk_bf16_f32 v22, v180, v181
	v_cvt_pk_bf16_f32 v23, v182, v183
	v_cvt_pk_bf16_f32 v24, v184, v185
	v_cvt_pk_bf16_f32 v25, v186, v187
	v_cvt_pk_bf16_f32 v6, v188, v189
	v_cvt_pk_bf16_f32 v7, v190, v191
	v_cvt_pk_bf16_f32 v8, v192, v193
	v_cvt_pk_bf16_f32 v9, v194, v195
	v_lshrrev_b32_e32 v179, 1, v179
	global_store_dwordx4 v179, v[128:131], s[12:13]
	global_store_dwordx4 v179, v[112:115], s[12:13] offset:256
	v_add_u32_e32 v178, 0x10000, v179
	global_store_dwordx4 v178, v[120:123], s[12:13]
	global_store_dwordx4 v178, v[96:99], s[12:13] offset:256
	v_add_u32_e32 v178, 0x20000, v179
	global_store_dwordx4 v178, v[108:111], s[12:13]
	global_store_dwordx4 v178, v[78:81], s[12:13] offset:256
	v_add_u32_e32 v178, 0x30000, v179
	global_store_dwordx4 v178, v[92:95], s[12:13]
	global_store_dwordx4 v178, v[70:73], s[12:13] offset:256
	v_add_u32_e32 v178, 0x80000, v179
	global_store_dwordx4 v178, v[62:65], s[12:13]
	global_store_dwordx4 v178, v[46:49], s[12:13] offset:256
	v_add_u32_e32 v178, 0x90000, v179
	global_store_dwordx4 v178, v[54:57], s[12:13]
	global_store_dwordx4 v178, v[30:33], s[12:13] offset:256
	v_add_u32_e32 v178, 0xa0000, v179
	global_store_dwordx4 v178, v[38:41], s[12:13]
	global_store_dwordx4 v178, v[14:17], s[12:13] offset:256
	v_add_u32_e32 v178, 0xb0000, v179
	global_store_dwordx4 v178, v[22:25], s[12:13]
	global_store_dwordx4 v178, v[6:9], s[12:13] offset:256
	s_nop 1
	s_cbranch_execz .LBB0_1625
